# M3 n_prev loads issued with the gate loads; attention passes keep the workspace pointer across passes instead of reloading it per pass
# speedup vs baseline: 1.0022x; 1.0022x over previous
.LBB0_68:
	s_mov_b64 s[8:9], s[36:37]
	v_mov_b32_e32 v187, v224
	s_ashr_i32 s0, s5, 7
	s_and_b32 s1, s5, 0x7f
	s_load_dwordx2 s[2:3], s[8:9], 0xa8
	s_lshl_b32 s14, s0, 13
	s_lshl_b32 s10, s1, 6
	s_waitcnt vmcnt(0)
	v_and_b32_e32 v2, 63, v187
	s_or_b32 s15, s10, s14
	v_or_b32_e32 v0, s15, v2
	v_ashrrev_i32_e32 v178, 7, v187
	v_ashrrev_i32_e32 v1, 31, v0
	v_ashrrev_i32_e32 v179, 31, v178
	s_waitcnt lgkmcnt(0)
	v_lshl_add_u64 v[0:1], v[0:1], 4, s[2:3]
	v_lshl_add_u64 v[0:1], v[178:179], 2, v[0:1]
	s_mov_b32 s10, 0x80000
	v_add_co_u32_e32 v4, vcc, s10, v0
	v_and_b32_e32 v162, 0xffffff80, v187
	s_nop 0
	v_addc_co_u32_e32 v5, vcc, 0, v1, vcc
	global_load_dword v3, v[4:5], off
	global_load_dword v6, v[0:1], off
	v_cmp_lt_i32_e32 vcc, v227, v237
	v_cmp_eq_u32_e64 s[38:39], 0, v2
	v_cmp_gt_u32_e64 s[40:41], 2, v2
	v_cndmask_b32_e32 v0, v227, v236, vcc
	v_lshlrev_b32_e32 v7, 2, v0
	v_cmp_lt_i32_e32 vcc, v228, v237
	v_lshl_add_u32 v0, s0, 9, v162
	v_or_b32_e32 v0, s1, v0
	v_cndmask_b32_e32 v1, v228, v236, vcc
	v_cmp_lt_i32_e32 vcc, v229, v237
	v_lshlrev_b32_e32 v8, 2, v1
	v_ashrrev_i32_e32 v1, 31, v0
	v_cndmask_b32_e32 v4, v229, v236, vcc
	v_lshlrev_b32_e32 v9, 2, v4
	v_lshl_add_u64 v[4:5], v[0:1], 2, s[2:3]
	s_mov_b32 s0, 0x104000
	v_add_co_u32_e32 v4, vcc, s0, v4
	v_cmp_gt_u32_e64 s[42:43], 4, v2
	s_nop 0
	v_addc_co_u32_e32 v5, vcc, 0, v5, vcc
	global_load_dword v36, v[4:5], off
	v_lshlrev_b64 v[214:215], 9, v[0:1]
	v_lshl_add_u64 v[214:215], s[2:3], 0, v[214:215]
	v_lshlrev_b32_e32 v216, 2, v2
	v_mov_b32_e32 v217, v113
	v_lshl_add_u64 v[214:215], v[214:215], 0, v[216:217]
	v_add_co_u32_e32 v214, vcc, 0x300000, v214
	s_nop 0
	v_addc_co_u32_e32 v215, vcc, 0, v215, vcc
	global_load_dword v218, v[214:215], off
	global_load_dword v219, v[214:215], off offset:256
	v_cmp_lt_i32_e32 vcc, v230, v237
	v_cmp_gt_u32_e64 s[44:45], 8, v2
	v_cmp_gt_u32_e64 s[46:47], 16, v2
	v_cndmask_b32_e32 v5, v230, v236, vcc
	v_cmp_lt_i32_e32 vcc, v231, v237
	v_lshl_add_u32 v37, v162, 2, s13
	s_waitcnt vmcnt(4)
	ds_bpermute_b32 v10, v7, v3
	s_waitcnt lgkmcnt(0)
	v_add_f32_e32 v10, v3, v10
	v_cndmask_b32_e64 v3, v10, v3, s[38:39]
	ds_bpermute_b32 v10, v8, v3
	s_waitcnt lgkmcnt(0)
	v_add_f32_e32 v4, v3, v10
	v_cndmask_b32_e64 v3, v4, v3, s[40:41]
	ds_bpermute_b32 v4, v9, v3
	v_lshlrev_b32_e32 v10, 2, v5
	v_cndmask_b32_e32 v5, v231, v236, vcc
	v_lshlrev_b32_e32 v11, 2, v5
	v_cmp_lt_i32_e32 vcc, v232, v237
	s_waitcnt lgkmcnt(0)
	v_add_f32_e32 v4, v3, v4
	v_cndmask_b32_e64 v3, v4, v3, s[42:43]
	ds_bpermute_b32 v4, v10, v3
	v_cndmask_b32_e32 v5, v232, v236, vcc
	v_lshlrev_b32_e32 v12, 2, v5
	v_cmp_gt_u32_e32 vcc, 32, v2
	s_waitcnt lgkmcnt(0)
	v_add_f32_e32 v4, v3, v4
	v_cndmask_b32_e64 v3, v4, v3, s[44:45]
	ds_bpermute_b32 v4, v11, v3
	s_waitcnt lgkmcnt(0)
	v_add_f32_e32 v4, v3, v4
	v_cndmask_b32_e64 v3, v4, v3, s[46:47]
	ds_bpermute_b32 v4, v12, v3
	s_waitcnt lgkmcnt(0)
	v_add_f32_e32 v4, v3, v4
	v_cndmask_b32_e32 v4, v4, v3, vcc
	s_waitcnt vmcnt(3)
	v_sub_f32_e32 v5, v6, v4
	ds_bpermute_b32 v3, v7, v5
	s_waitcnt lgkmcnt(0)
	v_max_f32_e32 v3, v3, v3
	v_max_f32_e32 v3, v5, v3
	v_cndmask_b32_e64 v3, v3, v5, s[38:39]
	ds_bpermute_b32 v6, v8, v3
	v_lshlrev_b32_e32 v8, 8, v178
	v_add_u32_e32 v39, s7, v8
	v_add_u32_e32 v38, s12, v8
	s_waitcnt lgkmcnt(0)
	v_max_f32_e32 v6, v6, v6
	v_max_f32_e32 v6, v3, v6
	v_cndmask_b32_e64 v3, v6, v3, s[40:41]
	ds_bpermute_b32 v6, v9, v3
	s_waitcnt lgkmcnt(0)
	v_max_f32_e32 v6, v6, v6
	v_max_f32_e32 v6, v3, v6
	v_cndmask_b32_e64 v3, v6, v3, s[42:43]
	ds_bpermute_b32 v6, v10, v3
	s_waitcnt lgkmcnt(0)
	v_max_f32_e32 v6, v6, v6
	v_max_f32_e32 v6, v3, v6
	v_cndmask_b32_e64 v6, v6, v3, s[44:45]
	ds_bpermute_b32 v7, v11, v6
	v_bfe_u32 v3, v187, 6, 1
	v_cmp_eq_u32_e64 s[38:39], 0, v3
	s_waitcnt lgkmcnt(0)
	v_max_f32_e32 v7, v7, v7
	v_max_f32_e32 v7, v6, v7
	v_cndmask_b32_e64 v6, v7, v6, s[46:47]
	ds_bpermute_b32 v7, v12, v6
	s_and_saveexec_b64 s[0:1], s[38:39]
	s_cbranch_execz .LBB0_70
	s_waitcnt lgkmcnt(0)
	v_max_f32_e32 v7, v7, v7
	v_max_f32_e32 v9, v6, v6
	v_max_f32_e32 v7, v9, v7
	v_lshlrev_b32_e32 v8, 6, v178
	v_cndmask_b32_e32 v6, v7, v6, vcc
	v_lshlrev_b32_e32 v8, 2, v8
	v_max_f32_e32 v6, v6, v6
	s_waitcnt vmcnt(0)
	v_max_f32_e32 v7, v36, v36
	v_lshlrev_b32_e32 v112, 2, v2
	v_max_f32_e32 v6, v7, v6
	v_add3_u32 v7, s6, v8, v112
	ds_write_b32 v7, v5
	v_add_u32_e32 v5, v39, v112
	v_add_f32_e32 v6, v4, v6
	ds_write_b32 v5, v4
	v_add_u32_e32 v4, v38, v112
	ds_write_b32 v4, v6
	v_lshlrev_b64 v[4:5], 9, v[0:1]
	v_lshl_add_u64 v[4:5], s[2:3], 0, v[4:5]
	v_lshl_add_u64 v[4:5], v[4:5], 0, v[112:113]
	s_mov_b64 s[10:11], 0x300000
	v_lshl_add_u64 v[6:7], v[4:5], 0, s[10:11]
	v_add_co_u32_e32 v4, vcc, 0x300000, v4
	s_nop 0
	v_addc_co_u32_e32 v5, vcc, 0, v5, vcc
	v_add_u32_e32 v5, v37, v112
	s_waitcnt vmcnt(0)
	ds_write2st64_b32 v5, v218, v219 offset1:1

.LBB0_259:
	s_or_b64 exec, exec, s[0:1]
	s_load_dwordx2 s[2:3], s[36:37], 0xa8
	v_readlane_b32 s0, v254, 21
	s_lshl_b32 s21, s0, 9
	s_lshl_b32 s0, s18, 3
	s_add_i32 s19, s24, 0x12000
	s_add_i32 s20, s24, 0x14800
	s_lshl_b32 s22, s18, 5
	s_lshl_b32 s23, s13, 5
	s_add_i32 s26, s0, 0xfffff000
	s_lshl_b32 s27, s13, 3
	s_waitcnt lgkmcnt(0)
	s_barrier
	s_mov_b32 s32, s18
	s_branch .LBB0_262

.LBB0_262:
	s_mov_b32 s18, s32
	s_sub_i32 s0, s32, 0x1c2
	s_cmp_lt_i32 s0, 39
	s_cbranch_scc1 .Lrd_done
	s_cmp_gt_i32 s0, 48
	s_cbranch_scc1 .Lrd_hi
	s_cmp_eq_u32 s0, 42
	s_cbranch_scc1 .Lrd_done
	s_cmp_eq_u32 s0, 46
	s_cbranch_scc1 .Lrd_done
	s_sub_i32 s1, s0, 39
	s_cmp_gt_i32 s0, 42
	s_cselect_b32 s5, 1, 0
	s_sub_i32 s1, s1, s5
	s_cmp_gt_i32 s0, 46
	s_cselect_b32 s5, 1, 0
	s_sub_i32 s1, s1, s5
	s_add_i32 s18, s1, 0x200
	s_branch .Lrd_done
.Lrd_hi:
	s_cmp_lt_i32 s0, 62
	s_cbranch_scc1 .Lrd_done
	s_sub_i32 s1, s0, 62
	s_cmp_gt_i32 s1, 2
	s_cselect_b32 s5, 1, 0
	s_add_i32 s6, s1, s5
	s_cmp_gt_i32 s1, 5
	s_cselect_b32 s5, 1, 0
	s_add_i32 s6, s6, s5
	s_add_i32 s18, s6, 0x1e9
.Lrd_done:
	s_lshl_b32 s22, s18, 5
	s_lshl_b32 s26, s18, 3
	s_add_i32 s26, s26, 0xfffff000
	s_cmpk_lt_i32 s18, 0x200
	s_mov_b64 s[0:1], -1
	s_cbranch_scc0 .LBB0_285
	s_mov_b64 s[8:9], s[36:37]
	v_mov_b32_e32 v12, v224
	s_and_b32 s6, s22, 0xffffe000
	s_bfe_u32 s7, s18, 0x70001
	v_ashrrev_i32_e32 v0, 6, v12
	s_movk_i32 s4, 0x2400
	s_waitcnt lgkmcnt(0)
	s_add_u32 s0, s2, 0x6000000
	s_addc_u32 s1, s3, 0
	v_mul_lo_u32 v4, v0, s4
	s_lshl_b32 s4, s18, 5
	v_and_b32_e32 v252, 31, v12
	v_mul_lo_u32 v0, v0, s61
	s_and_b32 s11, s4, 0xffffe000
	s_lshl_b32 s5, s7, 6
	s_and_b32 s10, s4, 32
	v_add_u32_e32 v246, s19, v0
	s_or_b32 s5, s5, s11
	v_or_b32_e32 v0, s10, v252
	s_waitcnt vmcnt(10)
	v_or_b32_e32 v162, s5, v0
	v_mov_b64_e32 v[0:1], s[0:1]
	s_movk_i32 s4, 0x1c00
	v_mad_i64_i32 v[0:1], s[4:5], v162, s4, v[0:1]
	s_sub_i32 s4, 8, s7
	s_cmp_lt_u32 s7, 8
	s_cselect_b32 s29, s4, 0
	s_add_i32 s4, s29, s7
	s_lshl_b32 s7, s4, 6
	v_and_b32_e32 v164, 0xffffffc0, v12
	s_add_i32 s4, s11, s7
	v_ashrrev_i32_e32 v165, 31, v164
	s_addk_i32 s4, 0xfe00
	v_bfe_u32 v13, v12, 5, 1
	v_lshlrev_b64 v[2:3], 1, v[164:165]
	s_mul_hi_i32 s5, s4, 0x1c00
	s_mulk_i32 s4, 0x1c00
	v_lshl_add_u64 v[0:1], v[0:1], 0, v[2:3]
	v_lshlrev_b32_e32 v112, 4, v13
	s_add_u32 s4, s0, s4
	v_lshl_add_u64 v[0:1], v[0:1], 0, v[112:113]
	v_add_u32_e32 v15, s24, v4
	s_addc_u32 s5, s1, s5
	v_mul_u32_u24_e32 v4, 0xe00, v252
	s_cmp_eq_u32 s43, 1
	s_cbranch_scc1 .Lpf_q_done
	global_load_dwordx4 v[64:67], v[0:1], off
	global_load_dwordx4 v[68:71], v[0:1], off offset:32
	global_load_dwordx4 v[72:75], v[0:1], off offset:64
	global_load_dwordx4 v[76:79], v[0:1], off offset:96
